# grid barrier: removed the per-XCD release counter add (write-only since members poll the top generation word), so XCD leaders no longer wait ~1us for its ack
# speedup vs baseline: 1.0082x; 1.0082x over previous
.LBB0_970:
	s_bcnt1_i32_b64 s2, s[2:3]
	v_mov_b32_e32 v0, s2
	v_readlane_b32 s2, v252, 60
	v_readlane_b32 s3, v252, 61
	s_nop 4
	s_getpc_b64 s[98:99]
